# G2 KV-up units rebalanced across workgroups (WGs with two Q-up units take one KV-up unit, the others three): 8/9 K-iterations per WG instead of 10/7
# speedup vs baseline: 1.0386x; 1.0063x over previous
.LBB0_854:
	s_add_i32 s90, s90, 1
	s_mul_i32 s4, s90, s29
	s_mul_hi_u32 s5, s90, s28
	s_add_i32 s5, s5, s4
	s_mul_i32 s4, s90, s28
	s_add_u32 s8, s4, s2
	s_addc_u32 s9, s5, s3
	s_mov_b64 s[100:101], s[86:87]
	s_cmp_eq_u32 s64, 0x400
	s_cbranch_scc0 .Lg2s_std
	s_lshl_b32 s8, s90, 7
	s_add_u32 s8, s8, s2
	s_mov_b32 s9, 0
	s_cmp_ge_u32 s2, 0x80
	s_movk_i32 s100, 0x80
	s_cselect_b32 s100, 0x200, s100
.Lg2s_std:
	v_mov_b64_e32 v[2:3], s[100:101]
	v_cmp_ge_i64_e64 s[4:5], s[8:9], v[2:3]
	v_cmp_lt_i64_e64 s[6:7], s[8:9], v[2:3]
	s_and_b64 vcc, exec, s[4:5]
	s_cbranch_vccnz .LBB0_856
	s_ashr_i32 s9, s8, 31
	s_lshr_b32 s9, s9, 29
	s_add_i32 s9, s8, s9
	s_ashr_i32 s38, s9, 3
	s_and_b32 s9, s9, -8
	s_sub_i32 s8, s8, s9
	s_lshr_b32 s9, s8, 31
	s_or_b32 s9, s55, s9
	s_mul_i32 s8, s9, s8
	s_add_i32 s8, s8, s38
	s_abs_i32 s38, s8
	s_mul_hi_u32 s39, s38, s62
	s_mul_i32 s40, s39, s65
	s_sub_i32 s38, s38, s40
	s_ashr_i32 s9, s8, 31
	s_add_i32 s40, s39, 1
	s_sub_i32 s41, s38, s65
	s_cmp_ge_u32 s38, s65
	s_cselect_b32 s39, s40, s39
	s_cselect_b32 s38, s41, s38
	s_add_i32 s40, s39, 1
	s_cmp_ge_u32 s38, s65
	s_cselect_b32 s38, s40, s39
	s_xor_b32 s38, s38, s9
	s_sub_i32 s9, s38, s9
	s_lshl_b32 s38, s9, 3
	s_sub_i32 s39, 0x80, s38
	s_min_i32 s39, s39, 8
	s_abs_i32 s40, s39
	v_cvt_f32_u32_e32 v0, s40
	s_sub_i32 s63, 0, s40
	s_mul_i32 s9, s9, s65
	s_sub_i32 s8, s8, s9
	v_rcp_iflag_f32_e32 v0, v0
	s_abs_i32 s41, s8
	s_xor_b32 s9, s8, s39
	s_ashr_i32 s9, s9, 31
	v_mul_f32_e32 v0, 0x4f7ffffe, v0
	v_cvt_u32_f32_e32 v0, v0
	s_nop 0
	v_readfirstlane_b32 s94, v0
	s_mul_i32 s63, s63, s94
	s_mul_hi_u32 s63, s94, s63
	s_add_i32 s94, s94, s63
	s_mul_hi_u32 s63, s41, s94
	s_mul_i32 s94, s63, s40
	s_sub_i32 s41, s41, s94
	s_add_i32 s94, s63, 1
	s_sub_i32 s95, s41, s40
	s_cmp_ge_u32 s41, s40
	s_cselect_b32 s63, s94, s63
	s_cselect_b32 s41, s95, s41
	s_add_i32 s94, s63, 1
	s_cmp_ge_u32 s41, s40
	s_cselect_b32 s40, s94, s63
	s_xor_b32 s40, s40, s9
	s_sub_i32 s94, s40, s9
	s_mul_i32 s9, s94, s39
	s_sub_i32 s8, s8, s9
	s_add_i32 s95, s8, s38
